# static s_setprio 1 for waves 4-7 during the mixer phase (LRU, attention, conv), reset before the next barrier
# baseline (speedup 1.0000x reference)
; #define LAS __attribute__((address_space(3)))
; __device__ __forceinline__ const float* gptr(const float* p) { return (const float*)(const __attribute__((address_space(1))) float*)p; }
; __device__ __forceinline__ int launder_v(int x) { asm volatile("" : "+v"(x)); return x; }
; __device__ __forceinline__ void lru_chain(unsigned char* ws_, const float* const* in_, int l_, LAS unsigned char* lds, int tid, int bid, int G) {
;     const MixCtx X = mk_mix(ws_, in_, l_); tid = launder_v(tid);
;     const int lane = tid & 63, w = __builtin_amdgcn_readfirstlane(tid >> 6); const int l = X.l;
;     LAS unsigned char* UB = lds + LR_UB; LAS float* A_ = (LAS float*)(lds + LR_A); LAS float* B_ = (LAS float*)(lds + LR_B);
;     LAS unsigned char* WT = lds + LR_WT; LAS float* PRM = (LAS float*)(lds + LR_PRM); LAS float* SA = (LAS float*)(lds + LR_SA); LAS float* SB = (LAS float*)(lds + LR_SB); LAS unsigned char* GT = lds + LR_GT;
;     LAS float* CAR = (LAS float*)(lds + LR_CAR);
;     const int cg8 = tid & 7, tp = tid >> 3; const int j = lane & 15, kq = lane >> 4;
;     for (int chain = bid; chain < BATCH * 6; chain += G) {
;         const int b = chain / 6, h = chain % 6, c0 = h * 64;
;         LruPre P; lru_load(X, b, h, 0, tid, P);
;         f32x4 cwv[4][2], cbv[2];
; #pragma unroll
;         for (int e2 = 0; e2 < 2; ++e2) { cbv[e2] = *(const f32x4*)(gptr(X.in[8]) + l * LW + c0 + 8 * cg8 + 4 * e2);
; #pragma unroll
;             for (int k = 0; k < 4; ++k) cwv[k][e2] = *(const f32x4*)(gptr(X.in[7]) + (size_t)(l * 4 + k) * LW + c0 + 8 * cg8 + 4 * e2); }
; __device__ __forceinline__ void mixer_phase(const Ctx& C, int l) {
;     lru_chain(C.ws, C.in, l, C.lds, C.tid, C.bid, C.G);
.LBB0_170:
	s_or_b64 exec, exec, s[28:29]
	s_mov_b64 s[2:3], 0
	s_waitcnt lgkmcnt(0)
	s_barrier
	s_mov_b64 s[62:63], 0
	v_readlane_b32 s2, v253, 8
	v_mov_b32_e32 v150, v139
	v_readlane_b32 s4, v254, 39
	v_readlane_b32 s3, v253, 9
	s_add_u32 s64, s2, s62
	s_mov_b64 s[26:27], 0
	s_mov_b32 s2, s48
	v_mov_b32_e32 v1, v150
	v_readlane_b32 s5, v254, 40
	s_addc_u32 s65, s3, s63
	s_andn2_b64 vcc, exec, s[4:5]
	v_readfirstlane_b32 s3, v1
	s_nop 3
	s_cmp_ge_u32 s3, 0x100
	s_cbranch_scc0 .Lmix_prio_done
	s_setprio 1
.Lmix_prio_done:
	s_cbranch_vccnz .LBB0_206
	s_add_u32 s4, s64, s26
	s_addc_u32 s5, s65, s27
	s_add_u32 s76, s4, 0xb500000
	s_addc_u32 s77, s5, 0
	s_add_u32 s46, s4, 0x1e500000
	v_ashrrev_i32_e32 v4, 2, v1
	s_addc_u32 s47, s5, 0
	v_and_b32_e32 v152, -2, v4
	s_add_u32 s78, s4, 0x100000
	v_add_u32_e32 v6, -3, v152
	s_addc_u32 s79, s5, 0
	v_mad_u64_u32 v[106:107], s[4:5], v6, s71, 0
	v_add_u32_e32 v6, -2, v152
	v_add_u32_e32 v8, 0x200, v1
	v_mad_u64_u32 v[108:109], s[4:5], v6, s71, 0
	v_add_u32_e32 v6, -1, v152
	v_or_b32_e32 v7, 1, v4
	v_ashrrev_i32_e32 v116, 3, v1
	v_ashrrev_i32_e32 v120, 3, v8
	v_mad_u64_u32 v[110:111], s[4:5], v6, s71, 0
	v_mad_u64_u32 v[112:113], s[4:5], v152, s71, 0
	v_mad_u64_u32 v[114:115], s[4:5], v7, s71, 0
	v_mad_i64_i32 v[118:119], s[4:5], v116, s71, 0
	v_mad_i64_i32 v[122:123], s[4:5], v120, s71, 0
	s_mul_i32 s4, s2, 0x180
	s_ashr_i32 s80, s3, 6
	s_ashr_i32 s5, s4, 31
	s_lshl_b32 s6, s2, 2
	s_add_i32 s7, 0, 0x1a000
	s_and_b32 s3, s3, 0x3fffffc0
	s_cmp_gt_i32 s80, 0
	s_cselect_b64 s[48:49], -1, 0
	s_cmp_eq_u32 s80, 7
	v_and_b32_e32 v3, 15, v1
	s_mul_i32 s81, s2, 6
	v_lshlrev_b32_e32 v9, 2, v1
	v_readlane_b32 s11, v255, 29
	s_cselect_b64 s[50:51], -1, 0
	s_mul_i32 s52, s2, 0x1800
	s_or_b32 s2, s6, 1
	v_and_b32_e32 v151, 63, v1
	v_add_u32_e32 v155, s7, v9
	v_add_u32_e32 v156, s11, v9
	v_lshl_or_b32 v9, s80, 4, v3
	s_mul_hi_i32 s55, s2, 0x600
	s_mul_i32 s54, s2, 0x600
	s_or_b32 s2, s6, 2
	v_and_b32_e32 v5, 7, v1
	v_lshlrev_b32_e32 v104, 3, v1
	v_lshlrev_b32_e32 v6, 4, v1
	v_cmp_gt_i32_e64 s[42:43], 64, v1
	v_add_u32_e32 v154, s4, v1
	v_mul_lo_u32 v12, v9, s73
	v_and_b32_e32 v161, 48, v1
	v_lshlrev_b32_e32 v1, 7, v9
	v_or_b32_e32 v9, s3, v151
	s_mul_hi_i32 s57, s2, 0x600
	s_mul_i32 s56, s2, 0x600
	s_or_b32 s2, s6, 3
	v_add_u32_e32 v160, 0, v12
	v_lshlrev_b32_e32 v9, 2, v9
	v_readlane_b32 s3, v255, 31
	s_mul_hi_i32 s59, s2, 0x600
	s_mul_i32 s58, s2, 0x600
	s_movk_i32 s2, 0x110
	v_add_u32_e32 v162, s3, v9
	v_mul_lo_u32 v15, v152, s2
	v_mul_lo_u32 v17, v7, s2
	v_readlane_b32 s2, v255, 33
	v_readlane_b32 s3, v255, 34
	v_add3_u32 v169, v160, v1, v161
	v_or_b32_e32 v1, 64, v161
	v_add_u32_e32 v170, s7, v1
	v_add_u32_e32 v171, s2, v1
	v_add_u32_e32 v172, s3, v1
	v_or_b32_e32 v1, 0x80, v161
	v_add_u32_e32 v173, s7, v1
	v_add_u32_e32 v192, s2, v1
	v_add_u32_e32 v193, s3, v1
	v_or_b32_e32 v1, 0xc0, v161
	v_add_u32_e32 v167, s2, v161
	v_add_u32_e32 v195, s2, v1
	s_mul_i32 s2, s80, 0x440
	v_readlane_b32 s26, v255, 32
	v_add_u32_e32 v168, s3, v161
	v_add_u32_e32 v194, s7, v1
	v_add_u32_e32 v196, s3, v1
	v_or_b32_e32 v1, s2, v151
	s_lshl_b64 s[2:3], s[4:5], 2
	v_and_b32_e32 v6, 0x70, v6
	v_readlane_b32 s10, v255, 28
	v_readlane_b32 s12, v255, 30
	v_lshlrev_b32_e32 v11, 2, v151
	v_add_u32_e32 v163, s26, v9
	v_lshlrev_b32_e32 v9, 1, v151
	s_add_u32 s2, s8, s2
	v_add_u32_e32 v153, s10, v6
	v_add_u32_e32 v157, s12, v6
	v_add_u32_e32 v159, s11, v11
	v_add_u32_e32 v12, s12, v9
	v_mul_lo_u32 v16, v7, s73
	v_mov_b32_e32 v7, s10
	s_addc_u32 s3, s9, s3
	v_readlane_b32 s8, v253, 10
	v_add_u32_e32 v13, 0, v9
	v_lshlrev_b32_e32 v124, 3, v8
	v_lshlrev_b32_e32 v8, 5, v5
	v_mov_b32_e32 v9, v0
	v_readlane_b32 s9, v253, 11
	v_readlane_b32 s10, v253, 12
	v_readlane_b32 s11, v253, 13
	v_readlane_b32 s12, v253, 14
	v_readlane_b32 s13, v253, 15
	v_readlane_b32 s14, v253, 16
	v_readlane_b32 s15, v253, 17
	v_readlane_b32 s16, v253, 18
	v_readlane_b32 s17, v253, 19
	v_readlane_b32 s18, v253, 20
	v_readlane_b32 s19, v253, 21
	v_readlane_b32 s20, v253, 22
	v_readlane_b32 s21, v253, 23
	v_readlane_b32 s22, v253, 24
	v_readlane_b32 s23, v253, 25
	v_lshlrev_b32_e32 v6, 4, v5
	v_add_u32_e32 v158, 0, v6
	v_lshl_add_u64 v[128:129], s[22:23], 0, v[8:9]
	v_readlane_b32 s8, v253, 26
	v_readlane_b32 s9, v253, 27
	v_readlane_b32 s12, v253, 30
	v_readlane_b32 s13, v253, 31
	v_readlane_b32 s14, v253, 32
	v_readlane_b32 s15, v253, 33
	v_readlane_b32 s16, v253, 34
	v_readlane_b32 s17, v253, 35
	v_and_b32_e32 v2, 56, v104
	v_cmp_lt_i32_e64 s[38:39], 1, v4
	v_cmp_lt_i32_e64 s[40:41], -1, v4
	v_lshlrev_b32_e32 v4, 3, v5
	v_add_u32_e32 v10, v158, v6
	s_mul_hi_i32 s53, s6, 0x600
	v_mul_lo_u32 v14, v152, s73
	v_mad_u32_u24 v3, v3, s73, v7
	s_mul_i32 s6, s80, 0x900
	v_readlane_b32 s18, v253, 36
	v_readlane_b32 s19, v253, 37
	s_mov_b64 s[8:9], s[12:13]
	s_mov_b64 s[12:13], s[16:17]
	v_mov_b32_e32 v7, v0
	v_cmp_lt_i32_e64 s[36:37], 2, v152
	v_ashrrev_i32_e32 v117, 31, v116
	v_ashrrev_i32_e32 v121, 31, v120
	v_mul_lo_u32 v164, v116, s73
	v_ashrrev_i32_e32 v105, 31, v104
	v_ashrrev_i32_e32 v125, 31, v124
	v_mul_lo_u32 v165, v120, s73
	v_add_u32_e32 v166, s7, v161
	v_lshl_add_u32 v197, v1, 2, 0
	v_lshl_add_u64 v[126:127], s[2:3], 0, v[8:9]
	s_mov_b64 s[14:15], s[18:19]
	v_lshl_add_u64 v[130:131], s[46:47], 0, v[6:7]
	v_add_u32_e32 v198, s26, v11
	v_lshlrev_b32_e32 v132, 1, v2
	v_add_u32_e32 v199, v158, v14
	v_add_u32_e32 v200, v10, v15
	v_add_u32_e32 v201, v158, v16
	v_add_u32_e32 v202, v10, v17
	v_add_u32_e32 v203, v3, v161
	v_add_u32_e32 v204, s6, v12
	v_add_u32_e32 v205, s6, v13
	v_lshlrev_b32_e32 v134, 1, v4
	s_mov_b32 s82, s96
	v_readlane_b32 s10, v253, 28
	v_readlane_b32 s11, v253, 29
	v_readlane_b32 s20, v253, 38
	v_readlane_b32 s21, v253, 39
	v_readlane_b32 s22, v253, 40
	v_readlane_b32 s23, v253, 41
	s_branch .LBB0_173

; __device__ __forceinline__ unsigned xb_add(unsigned* p, unsigned v) { return __hip_atomic_fetch_add(p, v, __ATOMIC_RELAXED, __HIP_MEMORY_SCOPE_AGENT); }
; __device__ __forceinline__ void xcd_barrier(const XcdBarrier& b) {
;     asm volatile("s_waitcnt vmcnt(0)" ::: "memory");
;     __syncthreads();
;     if (threadIdx.x == 0) {
;         unsigned* bar = b.bar;
;         __builtin_amdgcn_s_waitcnt(0);
;         unsigned nloc = b.st[0], nx = b.st[1];
;         if (nloc == 0u) { xcd_barrier_complete(bar, b.x, nloc, nx); b.st[0] = nloc; b.st[1] = nx; }
;         const unsigned old = xb_add(&bar[XB_XSUB(b.x)], 1u);
.LBB0_305:
	s_setprio 0
	s_waitcnt vmcnt(0)
	s_barrier
	s_mov_b64 s[28:29], exec
	v_readlane_b32 s8, v253, 26
	v_readlane_b32 s10, v253, 28
	v_readlane_b32 s11, v253, 29
	v_readlane_b32 s2, v253, 43
	v_readlane_b32 s12, v253, 30
	v_readlane_b32 s13, v253, 31
	v_readlane_b32 s14, v253, 32
	v_readlane_b32 s15, v253, 33
	v_readlane_b32 s16, v253, 34
	v_readlane_b32 s17, v253, 35
	v_readlane_b32 s18, v253, 36
	v_readlane_b32 s19, v253, 37
	v_readlane_b32 s20, v253, 38
	v_readlane_b32 s21, v253, 39
	v_readlane_b32 s22, v253, 40
	v_readlane_b32 s23, v253, 41
	v_readlane_b32 s10, v255, 19
	v_readlane_b32 s3, v253, 44
	v_readlane_b32 s11, v255, 20
	v_readlane_b32 s12, v255, 35
	v_readlane_b32 s14, v255, 37
	v_readlane_b32 s16, v255, 39
	v_readlane_b32 s18, v255, 41
	v_readlane_b32 s20, v255, 43
	v_readlane_b32 s22, v255, 45
	v_readlane_b32 s50, v255, 47
	v_readlane_b32 s6, v255, 49
	v_readlane_b32 s46, v255, 51
	v_readlane_b32 s48, v253, 47
	s_and_b64 s[2:3], s[28:29], s[2:3]
	v_readlane_b32 s9, v253, 27
	v_readlane_b32 s11, v255, 57
	v_readlane_b32 s13, v255, 36
	v_readlane_b32 s15, v255, 38
	v_readlane_b32 s17, v255, 40
	v_readlane_b32 s19, v255, 42
	v_readlane_b32 s21, v255, 44
	v_readlane_b32 s23, v255, 46
	v_readlane_b32 s51, v255, 48
	v_readlane_b32 s7, v255, 50
	v_readlane_b32 s47, v255, 52
	v_readlane_b32 s49, v253, 48
	s_mov_b64 exec, s[2:3]
	s_cbranch_execz .LBB0_357
	v_readlane_b32 s2, v255, 26
	s_waitcnt vmcnt(0) expcnt(0) lgkmcnt(0)
	s_nop 0
	v_mov_b32_e32 v1, s2
	ds_read_b32 v3, v1
	v_readlane_b32 s2, v255, 27
	s_waitcnt lgkmcnt(0)
	v_cmp_ne_u32_e32 vcc, 0, v3
	v_mov_b32_e32 v1, s2
	ds_read_b32 v2, v1
	s_cbranch_vccnz .LBB0_321
	s_mov_b32 s2, 1
	s_branch .LBB0_309
